# last layer GEMM-1: skips the 40 context-row tiles per XCD class whose outputs are unused (r columns, MLA/GQA query columns); balanced enumeration
# speedup vs baseline: 1.1540x; 1.0037x over previous
; DEV int bid_() { int b = blockIdx.x; asm volatile("" : "+s"(b)); return b; }
; __device__ void phase_gemm1(PRef p, bf16* sA, bf16* sB) {
;   const int xcd_ = bid_() & 7, per_ = gridDim.x >> 3;
;   for (int t = bid_() >> 3; t < 36 * 24; t += per_) {
;     int rt = xcd_ + 8 * (t / 24), ct = t % 24;
;     f32x16 acc[2][2];
;     zero_acc<2>(acc);
;     gemm_tile<2>(acc, p.HY + (size_t)rt * 128 * 1024, 1024, p.WT1 + (size_t)ct * 128 * 1024, 1024, 1024, sA, sB);
;     bf16* dst;
;     int ld, c0;
;     if (ct < 14) { dst = p.ZA; ld = 1792; c0 = ct * 128; }
;     else if (ct < 18) { dst = p.ZB; ld = 512; c0 = (ct - 14) * 128; }
;     else { dst = p.ZC; ld = 768; c0 = (ct - 18) * 128; }
;     stage_tile<2>(acc, sA);
;     TILE_CHUNKS(2, sA, { *(u32x4*)(dst + (size_t)(rt * 128 + trow) * ld + c0 + tcol) = cv; })
;   }
.LBB0_304:
	v_mov_b32_e32 v0, v196
	s_load_dwordx2 s[12:13], s[20:21], 0x0
	v_cvt_pk_bf16_f32 v52, v52, v53
	v_lshrrev_b32_e32 v1, 1, v0
	v_and_b32_e32 v2, 31, v0
	v_and_or_b32 v1, v1, s75, v2
	v_and_b32_e32 v2, 64, v0
	v_lshrrev_b32_e32 v0, 2, v0
	v_and_b32_e32 v0, 8, v0
	v_lshl_or_b32 v0, v2, 1, v0
	v_mad_u64_u32 v[0:1], s[0:1], v1, s52, v[0:1]
	v_cvt_pk_bf16_f32 v53, v54, v55
	v_cvt_pk_bf16_f32 v54, v56, v57
	v_cvt_pk_bf16_f32 v55, v58, v59
	v_cvt_pk_bf16_f32 v36, v36, v37
	v_cvt_pk_bf16_f32 v37, v38, v39
	v_cvt_pk_bf16_f32 v38, v40, v41
	v_cvt_pk_bf16_f32 v39, v42, v43
	s_waitcnt lgkmcnt(0)
	s_barrier
	ds_write2_b64 v0, v[52:53], v[54:55] offset1:2
	v_cvt_pk_bf16_f32 v52, v60, v61
	v_cvt_pk_bf16_f32 v53, v62, v63
	v_cvt_pk_bf16_f32 v54, v64, v65
	v_cvt_pk_bf16_f32 v55, v66, v67
	ds_write2_b64 v0, v[36:37], v[38:39] offset0:8 offset1:10
	v_cvt_pk_bf16_f32 v36, v44, v45
	v_cvt_pk_bf16_f32 v37, v46, v47
	v_cvt_pk_bf16_f32 v38, v48, v49
	v_cvt_pk_bf16_f32 v39, v50, v51
	v_cvt_pk_bf16_f32 v20, v20, v21
	v_cvt_pk_bf16_f32 v21, v22, v23
	v_cvt_pk_bf16_f32 v22, v24, v25
	v_cvt_pk_bf16_f32 v23, v26, v27
	v_add_u32_e32 v2, 0x2000, v0
	ds_write2_b64 v0, v[52:53], v[54:55] offset0:4 offset1:6
	ds_write2_b64 v0, v[36:37], v[38:39] offset0:12 offset1:14
	ds_write2_b64 v2, v[20:21], v[22:23] offset0:64 offset1:66
	v_cvt_pk_bf16_f32 v0, v28, v29
	v_cvt_pk_bf16_f32 v1, v30, v31
	v_cvt_pk_bf16_f32 v20, v32, v33
	v_cvt_pk_bf16_f32 v21, v34, v35
	ds_write2_b64 v2, v[0:1], v[20:21] offset0:68 offset1:70
	v_cvt_pk_bf16_f32 v0, v4, v5
	v_cvt_pk_bf16_f32 v1, v6, v7
	v_cvt_pk_bf16_f32 v4, v8, v9
	v_cvt_pk_bf16_f32 v5, v10, v11
	ds_write2_b64 v2, v[0:1], v[4:5] offset0:72 offset1:74
	v_cvt_pk_bf16_f32 v0, v12, v13
	v_cvt_pk_bf16_f32 v1, v14, v15
	v_cvt_pk_bf16_f32 v4, v16, v17
	v_cvt_pk_bf16_f32 v5, v18, v19
	ds_write2_b64 v2, v[0:1], v[4:5] offset0:76 offset1:78
	v_mov_b32_e32 v2, v196
	s_waitcnt lgkmcnt(0)
	s_barrier
	s_lshl_b32 s20, s10, 7
	s_ashr_i32 s19, s18, 31
	s_lshl_b64 s[0:1], s[18:19], 1
	s_add_u32 s10, s12, s0
	s_addc_u32 s11, s13, s1
	s_mul_hi_u32 s1, s20, s14
	s_mul_i32 s0, s20, s14
	s_lshl_b64 s[0:1], s[0:1], 1
	s_add_u32 s98, s10, s0
	s_addc_u32 s99, s11, s1
	s_lshl_b32 s1, s14, 5
	v_lshrrev_b32_e32 v60, 4, v196
	v_and_b32_e32 v61, 15, v196
	v_mul_lo_u32 v62, v60, s52
	v_lshl_add_u32 v62, v61, 4, v62
	v_mul_lo_u32 v63, v60, s14
	v_lshlrev_b32_e32 v63, 1, v63
	v_lshl_add_u32 v63, v61, 4, v63
	ds_read_b128 v[20:23], v62 offset:0
	ds_read_b128 v[24:27], v62 offset:4352
	ds_read_b128 v[28:31], v62 offset:8704
	ds_read_b128 v[32:35], v62 offset:13056
	ds_read_b128 v[36:39], v62 offset:17408
	ds_read_b128 v[40:43], v62 offset:21760
	ds_read_b128 v[44:47], v62 offset:26112
	ds_read_b128 v[48:51], v62 offset:30464
	s_waitcnt lgkmcnt(7)
	global_store_dwordx4 v63, v[20:23], s[98:99]
	s_add_u32 s98, s98, s1
	s_addc_u32 s99, s99, 0
	s_waitcnt lgkmcnt(6)
	global_store_dwordx4 v63, v[24:27], s[98:99]
	s_add_u32 s98, s98, s1
	s_addc_u32 s99, s99, 0
	s_waitcnt lgkmcnt(5)
	global_store_dwordx4 v63, v[28:31], s[98:99]
	s_add_u32 s98, s98, s1
	s_addc_u32 s99, s99, 0
	s_waitcnt lgkmcnt(4)
	global_store_dwordx4 v63, v[32:35], s[98:99]
	s_add_u32 s98, s98, s1
	s_addc_u32 s99, s99, 0
	s_waitcnt lgkmcnt(3)
	global_store_dwordx4 v63, v[36:39], s[98:99]
	s_add_u32 s98, s98, s1
	s_addc_u32 s99, s99, 0
	s_waitcnt lgkmcnt(2)
	global_store_dwordx4 v63, v[40:43], s[98:99]
	s_add_u32 s98, s98, s1
	s_addc_u32 s99, s99, 0
	s_waitcnt lgkmcnt(1)
	global_store_dwordx4 v63, v[44:47], s[98:99]
	s_add_u32 s98, s98, s1
	s_addc_u32 s99, s99, 0
	s_waitcnt lgkmcnt(0)
	global_store_dwordx4 v63, v[48:51], s[98:99]
	s_add_i32 s24, s24, s81
	s_movk_i32 s0, 0x360
	s_cmp_eq_u32 s36, 0
	s_cselect_b32 s0, s0, 0x338
	s_cmp_lt_i32 s24, s0
	s_cbranch_scc0 .LBB0_319
.LBB0_305:
	s_cmp_eq_u32 s36, 0
	s_cbranch_scc1 .Lg1e_l0
	s_lshr_b32 s13, s25, 1
	s_cmpk_lt_u32 s24, 0x300
	s_cbranch_scc0 .Lg1e_ctx
	s_mul_hi_i32 s0, s24, 0x2aaaaaab
	s_lshr_b32 s1, s0, 31
	s_ashr_i32 s0, s0, 2
	s_add_i32 s0, s0, s1
	s_mul_i32 s1, s0, 24
	s_sub_i32 s12, s24, s1
	s_mov_b32 s14, 0xf7fbfdfe
	s_mov_b32 s15, 15
	s_cmp_eq_u32 s13, 1
	s_cselect_b32 s14, 0xdfeff7fb, s14
	s_cmp_eq_u32 s13, 2
	s_cselect_b32 s14, 0x7fbfdfef, s14
	s_cmp_eq_u32 s13, 3
	s_cselect_b32 s14, 0xfeff7fbf, s14
	s_cselect_b32 s15, 13, s15
	s_branch .Lg1e_nth
.Lg1e_ctx:
	s_sub_u32 s1, s24, 0x300
	s_mul_i32 s0, s1, 37
	s_lshr_b32 s0, s0, 9
	s_mul_i32 s12, s0, 14
	s_sub_u32 s12, s1, s12
	s_add_u32 s1, s12, 4
	s_cmp_gt_u32 s12, 9
	s_cselect_b32 s11, 2, 0
	s_add_u32 s1, s1, s11
	s_cmp_gt_u32 s12, 11
	s_cselect_b32 s11, 4, 0
	s_add_u32 s12, s1, s11
	s_mov_b32 s14, 0x8040201
	s_mov_b32 s15, 0
	s_cmp_eq_u32 s13, 1
	s_cselect_b32 s14, 0x20100804, s14
	s_cmp_eq_u32 s13, 2
	s_cselect_b32 s14, 0x80402010, s14
	s_cmp_eq_u32 s13, 3
	s_cselect_b32 s14, 0x1008040, s14
	s_cselect_b32 s15, 2, s15

; DEV int bid_() { int b = blockIdx.x; asm volatile("" : "+s"(b)); return b; }
; __device__ void phase_gemm1(PRef p, bf16* sA, bf16* sB) {
;     ...
;   for (int t = bid_() >> 3; t < 36 * 24; t += per_) {
;     int rt = xcd_ + 8 * (t / 24), ct = t % 24;
.Lg1e_clr:
	s_add_u32 s10, s14, -1
	s_addc_u32 s11, s15, -1
	s_and_b64 s[14:15], s[14:15], s[10:11]
	s_sub_u32 s0, s0, 1
	s_cmp_lg_u32 s0, 0
	s_cbranch_scc1 .Lg1e_clr
.Lg1e_ff:
	s_ff1_i32_b64 s0, s[14:15]
	s_lshl_b32 s0, s0, 3
	s_or_b32 s10, s0, s25
	s_branch .Lg1e_done

; DEV int tid_() { int t = threadIdx.x; asm volatile("" : "+v"(t)); return t; }
; template <int NI, bool DEEP = true>
; DEV void gemm_tile(f32x16 (&acc)[2][NI], const bf16* __restrict__ A, int lda, const bf16* __restrict__ Bt, int ldb,
;                    int K, bf16* sA, bf16* sB) {
;   int tid = tid_(), lane = tid & 63, wave = tid >> 6;
;   int wm = wave >> 1, wn = wave & 1;
;   int lr = tid >> 3, lc = (tid & 7) * 8;
;   const bf16* Ap = A + (size_t)lr * lda + lc;
;   const bf16* Bp = Bt + (size_t)lr * ldb + lc;
;   u32x4 ra0[4], rb0[2 * NI], ra1[4], rb1[2 * NI];
; __device__ void phase_gemm1(PRef p, bf16* sA, bf16* sB) {
;     ...
;     int rt = xcd_ + 8 * (t / 24), ct = t % 24;
;     f32x16 acc[2][2];
;     zero_acc<2>(acc);
;     gemm_tile<2>(acc, p.HY + (size_t)rt * 128 * 1024, 1024, p.WT1 + (size_t)ct * 128 * 1024, 1024, 1024, sA, sB);
.Lg1e_done:
	s_lshl_b32 s0, s10, 18
	s_add_u32 s98, s86, s0
	s_addc_u32 s99, s87, 0
	s_lshl_b32 s0, s12, 18
	s_waitcnt lgkmcnt(0)
	s_add_u32 s100, s4, s0
	s_addc_u32 s101, s5, 0
	v_and_b32_e32 v0, 63, v196
	v_lshrrev_b32_e32 v1, 6, v196
	v_lshrrev_b32_e32 v2, 3, v0
	v_readfirstlane_b32 s16, v1
	v_lshrrev_b32_e32 v78, 1, v2
	v_and_b32_e32 v79, 7, v0
	v_xor_b32_e32 v78, v79, v78
	v_lshlrev_b32_e32 v78, 4, v78
	v_lshl_or_b32 v68, v2, 11, v78
	v_xor_b32_e32 v69, 64, v68
	v_lshrrev_b32_e32 v78, 5, v0
	v_bfe_u32 v79, v0, 1, 3
	v_and_b32_e32 v2, 31, v0
	v_lshrrev_b32_e32 v0, 1, v1
	v_and_b32_e32 v1, 1, v1
	v_lshl_add_u32 v0, v0, 6, v2
	v_lshl_add_u32 v1, v1, 6, v2
	v_lshlrev_b32_e32 v0, 7, v0
	v_lshlrev_b32_e32 v1, 7, v1
	v_add_u32_e32 v1, 0x4000, v1
	v_add_u32_e32 v2, 0, v78
	v_xor_b32_e32 v2, v2, v79
	v_lshl_add_u32 v70, v2, 4, v0
	v_lshl_add_u32 v74, v2, 4, v1
	v_add_u32_e32 v2, 2, v78
	v_xor_b32_e32 v2, v2, v79
	v_lshl_add_u32 v71, v2, 4, v0
	v_lshl_add_u32 v75, v2, 4, v1
	v_add_u32_e32 v2, 4, v78
	v_xor_b32_e32 v2, v2, v79
	v_lshl_add_u32 v72, v2, 4, v0
	v_lshl_add_u32 v76, v2, 4, v1
	v_add_u32_e32 v2, 6, v78
	v_xor_b32_e32 v2, v2, v79
	v_lshl_add_u32 v73, v2, 4, v0
	v_lshl_add_u32 v77, v2, 4, v1
	s_lshl_b32 s17, s16, 16
	s_lshl_b32 s16, s16, 12
	s_add_u32 s98, s98, s17
	s_addc_u32 s99, s99, 0
	s_add_u32 s100, s100, s17
	s_addc_u32 s101, s101, 0
	s_waitcnt lgkmcnt(0)
	s_barrier
	s_add_u32 m0, s16, 0x0
	s_nop 0
	global_load_lds_dwordx4 v68, s[98:99]
	s_add_u32 m0, s16, 0x400
	s_add_u32 s14, s98, 0x4000
	s_addc_u32 s15, s99, 0
	global_load_lds_dwordx4 v69, s[14:15]
	s_add_u32 m0, s16, 0x800
	s_add_u32 s14, s98, 0x8000
	s_addc_u32 s15, s99, 0
	global_load_lds_dwordx4 v68, s[14:15]
	s_add_u32 m0, s16, 0xc00
	s_add_u32 s14, s98, 0xc000
	s_addc_u32 s15, s99, 0
	global_load_lds_dwordx4 v69, s[14:15]
	s_add_u32 m0, s16, 0x4000
	s_nop 0
	global_load_lds_dwordx4 v68, s[100:101]
	s_add_u32 m0, s16, 0x4400
	s_add_u32 s14, s100, 0x4000
	s_addc_u32 s15, s101, 0
	global_load_lds_dwordx4 v69, s[14:15]
	s_add_u32 m0, s16, 0x4800
	s_add_u32 s14, s100, 0x8000
	s_addc_u32 s15, s101, 0
	global_load_lds_dwordx4 v68, s[14:15]
	s_add_u32 m0, s16, 0x4c00
	s_add_u32 s14, s100, 0xc000
	s_addc_u32 s15, s101, 0
	global_load_lds_dwordx4 v69, s[14:15]
	s_add_u32 s98, s98, 0x80
	s_addc_u32 s99, s99, 0
	s_add_u32 s100, s100, 0x80
	s_addc_u32 s101, s101, 0
	v_mov_b32_e32 v4, 0
	v_mov_b32_e32 v5, 0
	v_mov_b32_e32 v6, 0
	v_mov_b32_e32 v7, 0
	v_mov_b32_e32 v8, 0
	v_mov_b32_e32 v9, 0
	v_mov_b32_e32 v10, 0
	v_mov_b32_e32 v11, 0
	v_mov_b32_e32 v12, 0
	v_mov_b32_e32 v13, 0
	v_mov_b32_e32 v14, 0
	v_mov_b32_e32 v15, 0
	v_mov_b32_e32 v16, 0
	v_mov_b32_e32 v17, 0
	v_mov_b32_e32 v18, 0
	v_mov_b32_e32 v19, 0
	v_mov_b32_e32 v20, 0
	v_mov_b32_e32 v21, 0
	v_mov_b32_e32 v22, 0
	v_mov_b32_e32 v23, 0
	v_mov_b32_e32 v24, 0
	v_mov_b32_e32 v25, 0
	v_mov_b32_e32 v26, 0
	v_mov_b32_e32 v27, 0
	v_mov_b32_e32 v28, 0
	v_mov_b32_e32 v29, 0
	v_mov_b32_e32 v30, 0
	v_mov_b32_e32 v31, 0
	v_mov_b32_e32 v32, 0
	v_mov_b32_e32 v33, 0
	v_mov_b32_e32 v34, 0
	v_mov_b32_e32 v35, 0
	v_mov_b32_e32 v36, 0
	v_mov_b32_e32 v37, 0
	v_mov_b32_e32 v38, 0
	v_mov_b32_e32 v39, 0
	v_mov_b32_e32 v40, 0
	v_mov_b32_e32 v41, 0
	v_mov_b32_e32 v42, 0
	v_mov_b32_e32 v43, 0
	v_mov_b32_e32 v44, 0
	v_mov_b32_e32 v45, 0
	v_mov_b32_e32 v46, 0
	v_mov_b32_e32 v47, 0
	v_mov_b32_e32 v48, 0
	v_mov_b32_e32 v49, 0
	v_mov_b32_e32 v50, 0
	v_mov_b32_e32 v51, 0
	v_mov_b32_e32 v52, 0
	v_mov_b32_e32 v53, 0
	v_mov_b32_e32 v54, 0
	v_mov_b32_e32 v55, 0
	v_mov_b32_e32 v56, 0
	v_mov_b32_e32 v57, 0
	v_mov_b32_e32 v58, 0
	v_mov_b32_e32 v59, 0
	v_mov_b32_e32 v60, 0
	v_mov_b32_e32 v61, 0
	v_mov_b32_e32 v62, 0
	v_mov_b32_e32 v63, 0
	v_mov_b32_e32 v64, 0
	v_mov_b32_e32 v65, 0
	v_mov_b32_e32 v66, 0
	v_mov_b32_e32 v67, 0
	s_mov_b32 s11, 0
